# scan16: counted lgkmcnt waits exclude only the ds_write (6/5/7)
# speedup vs baseline: 1.0095x; 1.0095x over previous
.LBB0_1632:
	s_andn2_b64 vcc, exec, s[34:35]
	s_movk_i32 s2, 0x700
	s_cbranch_vccnz .LBB0_1634
	s_movk_i32 s2, 0xf00
	v_add_f32_dpp v234, v63, v63 quad_perm:[1,0,3,2] row_mask:0xf bank_mask:0xf bound_ctrl:1
	v_mov_b32_e32 v240, v53
	s_nop 0
	v_add_f32_dpp v234, v234, v234 quad_perm:[2,3,0,1] row_mask:0xf bank_mask:0xf bound_ctrl:1
	s_nop 1
	v_add_f32_dpp v234, v234, v234 row_half_mirror row_mask:0xf bank_mask:0xf bound_ctrl:1
	s_nop 1
	v_add_f32_dpp v234, v234, v234 row_mirror row_mask:0xf bank_mask:0xf bound_ctrl:1
	v_pk_fma_f32 v[36:37], v[32:33], v[234:235], v[54:55] op_sel_hi:[1,0,1]
	v_pk_fma_f32 v[34:35], v[30:31], v[234:235], v[56:57] op_sel_hi:[1,0,1]
	ds_read_b128 v[224:227], v51 offset:3840
	s_waitcnt lgkmcnt(6)
	v_pk_mul_f32 v[232:233], v[28:29], v[36:37]
	v_pk_fma_f32 v[232:233], v[26:27], v[34:35], v[232:233]
	ds_read_b128 v[64:67], v51 offset:3328
	ds_read_b128 v[68:71], v51 offset:3584
	v_add_f32_e32 v234, v232, v233
	v_pk_mul_f32 v[236:237], v[24:25], v[36:37]
	v_pk_fma_f32 v[236:237], v[22:23], v[34:35], v[236:237]
	v_add_f32_dpp v234, v234, v234 quad_perm:[1,0,3,2] row_mask:0xf bank_mask:0xf bound_ctrl:1
	s_waitcnt lgkmcnt(5)
	v_pk_mul_f32 v[228:229], v[18:19], v[34:35]
	v_add_f32_e32 v238, v236, v237
	v_add_f32_dpp v234, v234, v234 quad_perm:[2,3,0,1] row_mask:0xf bank_mask:0xf bound_ctrl:1
	v_pk_mul_f32 v[230:231], v[20:21], v[36:37]
	v_pk_fma_f32 v[56:57], v[14:15], v[240:241], v[228:229] op_sel_hi:[1,0,1]
	v_add_f32_dpp v234, v234, v234 row_half_mirror row_mask:0xf bank_mask:0xf bound_ctrl:1
	v_pk_fma_f32 v[54:55], v[16:17], v[240:241], v[230:231] op_sel_hi:[1,0,1]
	v_add_f32_dpp v238, v238, v238 quad_perm:[1,0,3,2] row_mask:0xf bank_mask:0xf bound_ctrl:1
	v_add_f32_dpp v234, v234, v234 row_mirror row_mask:0xf bank_mask:0xf bound_ctrl:1
	ds_read_b32 v242, v62 offset:4352
	ds_read_b128 v[30:33], v51 offset:4096
	ds_read_b128 v[22:25], v51 offset:3072
	s_waitcnt lgkmcnt(7)
	v_pk_fma_f32 v[36:37], v[12:13], v[234:235], v[54:55] op_sel_hi:[1,0,1]
	v_pk_fma_f32 v[34:35], v[10:11], v[234:235], v[56:57] op_sel_hi:[1,0,1]
	v_add_f32_dpp v238, v238, v238 quad_perm:[2,3,0,1] row_mask:0xf bank_mask:0xf bound_ctrl:1
	ds_write_b32 v49, v238
	ds_read_b128 v[26:29], v51 offset:5376
	s_waitcnt lgkmcnt(6)
	v_pk_mul_f32 v[232:233], v[226:227], v[36:37]
	v_pk_fma_f32 v[232:233], v[224:225], v[34:35], v[232:233]
	ds_read_b128 v[18:21], v51 offset:4864
	ds_read_b128 v[14:17], v51 offset:5120
	v_add_f32_e32 v234, v232, v233
	v_pk_mul_f32 v[236:237], v[8:9], v[36:37]
	v_pk_fma_f32 v[236:237], v[6:7], v[34:35], v[236:237]
	v_add_f32_dpp v234, v234, v234 quad_perm:[1,0,3,2] row_mask:0xf bank_mask:0xf bound_ctrl:1
	s_waitcnt lgkmcnt(5)
	v_pk_mul_f32 v[228:229], v[64:65], v[34:35]
	v_add_f32_e32 v238, v236, v237
	v_add_f32_dpp v234, v234, v234 quad_perm:[2,3,0,1] row_mask:0xf bank_mask:0xf bound_ctrl:1
	v_pk_mul_f32 v[230:231], v[66:67], v[36:37]
	v_pk_fma_f32 v[56:57], v[68:69], v[242:243], v[228:229] op_sel_hi:[1,0,1]
	v_add_f32_dpp v234, v234, v234 row_half_mirror row_mask:0xf bank_mask:0xf bound_ctrl:1
	v_pk_fma_f32 v[54:55], v[70:71], v[242:243], v[230:231] op_sel_hi:[1,0,1]
	v_add_f32_dpp v238, v238, v238 quad_perm:[1,0,3,2] row_mask:0xf bank_mask:0xf bound_ctrl:1
	v_add_f32_dpp v234, v234, v234 row_mirror row_mask:0xf bank_mask:0xf bound_ctrl:1
	ds_read_b32 v240, v62 offset:5888
	ds_read_b128 v[10:13], v51 offset:5632
	ds_read_b128 v[6:9], v51 offset:4608
	s_waitcnt lgkmcnt(7)
	v_pk_fma_f32 v[36:37], v[32:33], v[234:235], v[54:55] op_sel_hi:[1,0,1]
	v_pk_fma_f32 v[34:35], v[30:31], v[234:235], v[56:57] op_sel_hi:[1,0,1]
	v_add_f32_dpp v238, v238, v238 quad_perm:[2,3,0,1] row_mask:0xf bank_mask:0xf bound_ctrl:1
	ds_write_b32 v49, v238 offset:256
	ds_read_b128 v[224:227], v51 offset:6912
	s_waitcnt lgkmcnt(6)
	v_pk_mul_f32 v[232:233], v[28:29], v[36:37]
	v_pk_fma_f32 v[232:233], v[26:27], v[34:35], v[232:233]
	ds_read_b128 v[64:67], v51 offset:6400
	ds_read_b128 v[68:71], v51 offset:6656
	v_add_f32_e32 v234, v232, v233
	v_pk_mul_f32 v[236:237], v[24:25], v[36:37]
	v_pk_fma_f32 v[236:237], v[22:23], v[34:35], v[236:237]
	v_add_f32_dpp v234, v234, v234 quad_perm:[1,0,3,2] row_mask:0xf bank_mask:0xf bound_ctrl:1
	s_waitcnt lgkmcnt(5)
	v_pk_mul_f32 v[228:229], v[18:19], v[34:35]
	v_add_f32_e32 v238, v236, v237
	v_add_f32_dpp v234, v234, v234 quad_perm:[2,3,0,1] row_mask:0xf bank_mask:0xf bound_ctrl:1
	v_pk_mul_f32 v[230:231], v[20:21], v[36:37]
	v_pk_fma_f32 v[56:57], v[14:15], v[240:241], v[228:229] op_sel_hi:[1,0,1]
	v_add_f32_dpp v234, v234, v234 row_half_mirror row_mask:0xf bank_mask:0xf bound_ctrl:1
	v_pk_fma_f32 v[54:55], v[16:17], v[240:241], v[230:231] op_sel_hi:[1,0,1]
	v_add_f32_dpp v238, v238, v238 quad_perm:[1,0,3,2] row_mask:0xf bank_mask:0xf bound_ctrl:1
	v_add_f32_dpp v234, v234, v234 row_mirror row_mask:0xf bank_mask:0xf bound_ctrl:1
	ds_read_b32 v242, v62 offset:7424
	ds_read_b128 v[30:33], v51 offset:7168
	ds_read_b128 v[22:25], v51 offset:6144
	s_waitcnt lgkmcnt(7)
	v_pk_fma_f32 v[36:37], v[12:13], v[234:235], v[54:55] op_sel_hi:[1,0,1]
	v_pk_fma_f32 v[34:35], v[10:11], v[234:235], v[56:57] op_sel_hi:[1,0,1]
	v_add_f32_dpp v238, v238, v238 quad_perm:[2,3,0,1] row_mask:0xf bank_mask:0xf bound_ctrl:1
	ds_write_b32 v49, v238 offset:512
	ds_read_b128 v[26:29], v51 offset:8448
	s_waitcnt lgkmcnt(6)
	v_pk_mul_f32 v[232:233], v[226:227], v[36:37]
	v_pk_fma_f32 v[232:233], v[224:225], v[34:35], v[232:233]
	ds_read_b128 v[18:21], v51 offset:7936
	ds_read_b128 v[14:17], v51 offset:8192
	v_add_f32_e32 v234, v232, v233
	v_pk_mul_f32 v[236:237], v[8:9], v[36:37]
	v_pk_fma_f32 v[236:237], v[6:7], v[34:35], v[236:237]
	v_add_f32_dpp v234, v234, v234 quad_perm:[1,0,3,2] row_mask:0xf bank_mask:0xf bound_ctrl:1
	s_waitcnt lgkmcnt(5)
	v_pk_mul_f32 v[228:229], v[64:65], v[34:35]
	v_add_f32_e32 v238, v236, v237
	v_add_f32_dpp v234, v234, v234 quad_perm:[2,3,0,1] row_mask:0xf bank_mask:0xf bound_ctrl:1
	v_pk_mul_f32 v[230:231], v[66:67], v[36:37]
	v_pk_fma_f32 v[56:57], v[68:69], v[242:243], v[228:229] op_sel_hi:[1,0,1]
	v_add_f32_dpp v234, v234, v234 row_half_mirror row_mask:0xf bank_mask:0xf bound_ctrl:1
	v_pk_fma_f32 v[54:55], v[70:71], v[242:243], v[230:231] op_sel_hi:[1,0,1]
	v_add_f32_dpp v238, v238, v238 quad_perm:[1,0,3,2] row_mask:0xf bank_mask:0xf bound_ctrl:1
	v_add_f32_dpp v234, v234, v234 row_mirror row_mask:0xf bank_mask:0xf bound_ctrl:1
	ds_read_b32 v240, v62 offset:8960
	ds_read_b128 v[10:13], v51 offset:8704
	ds_read_b128 v[6:9], v51 offset:7680
	s_waitcnt lgkmcnt(7)
	v_pk_fma_f32 v[36:37], v[32:33], v[234:235], v[54:55] op_sel_hi:[1,0,1]
	v_pk_fma_f32 v[34:35], v[30:31], v[234:235], v[56:57] op_sel_hi:[1,0,1]
	v_add_f32_dpp v238, v238, v238 quad_perm:[2,3,0,1] row_mask:0xf bank_mask:0xf bound_ctrl:1
	ds_write_b32 v49, v238 offset:768
	ds_read_b128 v[224:227], v51 offset:9984
	s_waitcnt lgkmcnt(6)
	v_pk_mul_f32 v[232:233], v[28:29], v[36:37]
	v_pk_fma_f32 v[232:233], v[26:27], v[34:35], v[232:233]
	ds_read_b128 v[64:67], v51 offset:9472
	ds_read_b128 v[68:71], v51 offset:9728
	v_add_f32_e32 v234, v232, v233
	v_pk_mul_f32 v[236:237], v[24:25], v[36:37]
	v_pk_fma_f32 v[236:237], v[22:23], v[34:35], v[236:237]
	v_add_f32_dpp v234, v234, v234 quad_perm:[1,0,3,2] row_mask:0xf bank_mask:0xf bound_ctrl:1
	s_waitcnt lgkmcnt(5)
	v_pk_mul_f32 v[228:229], v[18:19], v[34:35]
	v_add_f32_e32 v238, v236, v237
	v_add_f32_dpp v234, v234, v234 quad_perm:[2,3,0,1] row_mask:0xf bank_mask:0xf bound_ctrl:1
	v_pk_mul_f32 v[230:231], v[20:21], v[36:37]
	v_pk_fma_f32 v[56:57], v[14:15], v[240:241], v[228:229] op_sel_hi:[1,0,1]
	v_add_f32_dpp v234, v234, v234 row_half_mirror row_mask:0xf bank_mask:0xf bound_ctrl:1
	v_pk_fma_f32 v[54:55], v[16:17], v[240:241], v[230:231] op_sel_hi:[1,0,1]
	v_add_f32_dpp v238, v238, v238 quad_perm:[1,0,3,2] row_mask:0xf bank_mask:0xf bound_ctrl:1
	v_add_f32_dpp v234, v234, v234 row_mirror row_mask:0xf bank_mask:0xf bound_ctrl:1
	ds_read_b32 v242, v62 offset:10496
	ds_read_b128 v[30:33], v51 offset:10240
	ds_read_b128 v[22:25], v51 offset:9216
	s_waitcnt lgkmcnt(7)
	v_pk_fma_f32 v[36:37], v[12:13], v[234:235], v[54:55] op_sel_hi:[1,0,1]
	v_pk_fma_f32 v[34:35], v[10:11], v[234:235], v[56:57] op_sel_hi:[1,0,1]
	v_add_f32_dpp v238, v238, v238 quad_perm:[2,3,0,1] row_mask:0xf bank_mask:0xf bound_ctrl:1
	ds_write_b32 v49, v238 offset:1024
	ds_read_b128 v[26:29], v51 offset:11520
	s_waitcnt lgkmcnt(6)
	v_pk_mul_f32 v[232:233], v[226:227], v[36:37]
	v_pk_fma_f32 v[232:233], v[224:225], v[34:35], v[232:233]
	ds_read_b128 v[18:21], v51 offset:11008
	ds_read_b128 v[14:17], v51 offset:11264
	v_add_f32_e32 v234, v232, v233
	v_pk_mul_f32 v[236:237], v[8:9], v[36:37]
	v_pk_fma_f32 v[236:237], v[6:7], v[34:35], v[236:237]
	v_add_f32_dpp v234, v234, v234 quad_perm:[1,0,3,2] row_mask:0xf bank_mask:0xf bound_ctrl:1
	s_waitcnt lgkmcnt(5)
	v_pk_mul_f32 v[228:229], v[64:65], v[34:35]
	v_add_f32_e32 v238, v236, v237
	v_add_f32_dpp v234, v234, v234 quad_perm:[2,3,0,1] row_mask:0xf bank_mask:0xf bound_ctrl:1
	v_pk_mul_f32 v[230:231], v[66:67], v[36:37]
	v_pk_fma_f32 v[56:57], v[68:69], v[242:243], v[228:229] op_sel_hi:[1,0,1]
	v_add_f32_dpp v234, v234, v234 row_half_mirror row_mask:0xf bank_mask:0xf bound_ctrl:1
	v_pk_fma_f32 v[54:55], v[70:71], v[242:243], v[230:231] op_sel_hi:[1,0,1]
	v_add_f32_dpp v238, v238, v238 quad_perm:[1,0,3,2] row_mask:0xf bank_mask:0xf bound_ctrl:1
	v_add_f32_dpp v234, v234, v234 row_mirror row_mask:0xf bank_mask:0xf bound_ctrl:1
	ds_read_b32 v240, v62 offset:12032
	ds_read_b128 v[10:13], v51 offset:11776
	ds_read_b128 v[6:9], v51 offset:10752
	s_waitcnt lgkmcnt(7)
	v_pk_fma_f32 v[36:37], v[32:33], v[234:235], v[54:55] op_sel_hi:[1,0,1]
	v_pk_fma_f32 v[34:35], v[30:31], v[234:235], v[56:57] op_sel_hi:[1,0,1]
	v_add_f32_dpp v238, v238, v238 quad_perm:[2,3,0,1] row_mask:0xf bank_mask:0xf bound_ctrl:1
	ds_write_b32 v49, v238 offset:1280
	ds_read_b128 v[224:227], v51 offset:13056
	s_waitcnt lgkmcnt(6)
	v_pk_mul_f32 v[232:233], v[28:29], v[36:37]
	v_pk_fma_f32 v[232:233], v[26:27], v[34:35], v[232:233]
	ds_read_b128 v[64:67], v51 offset:12544
	ds_read_b128 v[68:71], v51 offset:12800
	v_add_f32_e32 v234, v232, v233
	v_pk_mul_f32 v[236:237], v[24:25], v[36:37]
	v_pk_fma_f32 v[236:237], v[22:23], v[34:35], v[236:237]
	v_add_f32_dpp v234, v234, v234 quad_perm:[1,0,3,2] row_mask:0xf bank_mask:0xf bound_ctrl:1
	s_waitcnt lgkmcnt(5)
	v_pk_mul_f32 v[228:229], v[18:19], v[34:35]
	v_add_f32_e32 v238, v236, v237
	v_add_f32_dpp v234, v234, v234 quad_perm:[2,3,0,1] row_mask:0xf bank_mask:0xf bound_ctrl:1
	v_pk_mul_f32 v[230:231], v[20:21], v[36:37]
	v_pk_fma_f32 v[56:57], v[14:15], v[240:241], v[228:229] op_sel_hi:[1,0,1]
	v_add_f32_dpp v234, v234, v234 row_half_mirror row_mask:0xf bank_mask:0xf bound_ctrl:1
	v_pk_fma_f32 v[54:55], v[16:17], v[240:241], v[230:231] op_sel_hi:[1,0,1]
	v_add_f32_dpp v238, v238, v238 quad_perm:[1,0,3,2] row_mask:0xf bank_mask:0xf bound_ctrl:1
	v_add_f32_dpp v234, v234, v234 row_mirror row_mask:0xf bank_mask:0xf bound_ctrl:1
	ds_read_b32 v242, v62 offset:13568
	ds_read_b128 v[30:33], v51 offset:13312
	ds_read_b128 v[22:25], v51 offset:12288
	s_waitcnt lgkmcnt(7)
	v_pk_fma_f32 v[36:37], v[12:13], v[234:235], v[54:55] op_sel_hi:[1,0,1]
	v_pk_fma_f32 v[34:35], v[10:11], v[234:235], v[56:57] op_sel_hi:[1,0,1]
	v_add_f32_dpp v238, v238, v238 quad_perm:[2,3,0,1] row_mask:0xf bank_mask:0xf bound_ctrl:1
	ds_write_b32 v49, v238 offset:1536
	ds_read_b128 v[26:29], v51 offset:14592
	s_waitcnt lgkmcnt(6)
	v_pk_mul_f32 v[232:233], v[226:227], v[36:37]
	v_pk_fma_f32 v[232:233], v[224:225], v[34:35], v[232:233]
	ds_read_b128 v[18:21], v51 offset:14080
	ds_read_b128 v[14:17], v51 offset:14336
	v_add_f32_e32 v234, v232, v233
	v_pk_mul_f32 v[236:237], v[8:9], v[36:37]
	v_pk_fma_f32 v[236:237], v[6:7], v[34:35], v[236:237]
	v_add_f32_dpp v234, v234, v234 quad_perm:[1,0,3,2] row_mask:0xf bank_mask:0xf bound_ctrl:1
	s_waitcnt lgkmcnt(5)
	v_pk_mul_f32 v[228:229], v[64:65], v[34:35]
	v_add_f32_e32 v238, v236, v237
	v_add_f32_dpp v234, v234, v234 quad_perm:[2,3,0,1] row_mask:0xf bank_mask:0xf bound_ctrl:1
	v_pk_mul_f32 v[230:231], v[66:67], v[36:37]
	v_pk_fma_f32 v[56:57], v[68:69], v[242:243], v[228:229] op_sel_hi:[1,0,1]
	v_add_f32_dpp v234, v234, v234 row_half_mirror row_mask:0xf bank_mask:0xf bound_ctrl:1
	v_pk_fma_f32 v[54:55], v[70:71], v[242:243], v[230:231] op_sel_hi:[1,0,1]
	v_add_f32_dpp v238, v238, v238 quad_perm:[1,0,3,2] row_mask:0xf bank_mask:0xf bound_ctrl:1
	v_add_f32_dpp v234, v234, v234 row_mirror row_mask:0xf bank_mask:0xf bound_ctrl:1
	ds_read_b32 v240, v62 offset:15104
	ds_read_b128 v[10:13], v51 offset:14848
	ds_read_b128 v[6:9], v51 offset:13824
	s_waitcnt lgkmcnt(7)
	v_pk_fma_f32 v[36:37], v[32:33], v[234:235], v[54:55] op_sel_hi:[1,0,1]
	v_pk_fma_f32 v[34:35], v[30:31], v[234:235], v[56:57] op_sel_hi:[1,0,1]
	v_add_f32_dpp v238, v238, v238 quad_perm:[2,3,0,1] row_mask:0xf bank_mask:0xf bound_ctrl:1
	ds_write_b32 v49, v238 offset:1792
	ds_read_b128 v[224:227], v51 offset:16128
	s_waitcnt lgkmcnt(6)
	v_pk_mul_f32 v[232:233], v[28:29], v[36:37]
	v_pk_fma_f32 v[232:233], v[26:27], v[34:35], v[232:233]
	ds_read_b128 v[64:67], v51 offset:15616
	ds_read_b128 v[68:71], v51 offset:15872
	v_add_f32_e32 v234, v232, v233
	v_pk_mul_f32 v[236:237], v[24:25], v[36:37]
	v_pk_fma_f32 v[236:237], v[22:23], v[34:35], v[236:237]
	v_add_f32_dpp v234, v234, v234 quad_perm:[1,0,3,2] row_mask:0xf bank_mask:0xf bound_ctrl:1
	s_waitcnt lgkmcnt(5)
	v_pk_mul_f32 v[228:229], v[18:19], v[34:35]
	v_add_f32_e32 v238, v236, v237
	v_add_f32_dpp v234, v234, v234 quad_perm:[2,3,0,1] row_mask:0xf bank_mask:0xf bound_ctrl:1
	v_pk_mul_f32 v[230:231], v[20:21], v[36:37]
	v_pk_fma_f32 v[56:57], v[14:15], v[240:241], v[228:229] op_sel_hi:[1,0,1]
	v_add_f32_dpp v234, v234, v234 row_half_mirror row_mask:0xf bank_mask:0xf bound_ctrl:1
	v_pk_fma_f32 v[54:55], v[16:17], v[240:241], v[230:231] op_sel_hi:[1,0,1]
	v_add_f32_dpp v238, v238, v238 quad_perm:[1,0,3,2] row_mask:0xf bank_mask:0xf bound_ctrl:1
	v_add_f32_dpp v234, v234, v234 row_mirror row_mask:0xf bank_mask:0xf bound_ctrl:1
	ds_read_b32 v242, v62 offset:16640
	ds_read_b128 v[30:33], v51 offset:16384
	ds_read_b128 v[22:25], v51 offset:15360
	s_waitcnt lgkmcnt(7)
	v_pk_fma_f32 v[36:37], v[12:13], v[234:235], v[54:55] op_sel_hi:[1,0,1]
	v_pk_fma_f32 v[34:35], v[10:11], v[234:235], v[56:57] op_sel_hi:[1,0,1]
	v_add_f32_dpp v238, v238, v238 quad_perm:[2,3,0,1] row_mask:0xf bank_mask:0xf bound_ctrl:1
	ds_write_b32 v49, v238 offset:2048
	ds_read_b128 v[26:29], v51 offset:17664
	s_waitcnt lgkmcnt(6)
	v_pk_mul_f32 v[232:233], v[226:227], v[36:37]
	v_pk_fma_f32 v[232:233], v[224:225], v[34:35], v[232:233]
	ds_read_b128 v[18:21], v51 offset:17152
	ds_read_b128 v[14:17], v51 offset:17408
	v_add_f32_e32 v234, v232, v233
	v_pk_mul_f32 v[236:237], v[8:9], v[36:37]
	v_pk_fma_f32 v[236:237], v[6:7], v[34:35], v[236:237]
	v_add_f32_dpp v234, v234, v234 quad_perm:[1,0,3,2] row_mask:0xf bank_mask:0xf bound_ctrl:1
	s_waitcnt lgkmcnt(5)
	v_pk_mul_f32 v[228:229], v[64:65], v[34:35]
	v_add_f32_e32 v238, v236, v237
	v_add_f32_dpp v234, v234, v234 quad_perm:[2,3,0,1] row_mask:0xf bank_mask:0xf bound_ctrl:1
	v_pk_mul_f32 v[230:231], v[66:67], v[36:37]
	v_pk_fma_f32 v[56:57], v[68:69], v[242:243], v[228:229] op_sel_hi:[1,0,1]
	v_add_f32_dpp v234, v234, v234 row_half_mirror row_mask:0xf bank_mask:0xf bound_ctrl:1
	v_pk_fma_f32 v[54:55], v[70:71], v[242:243], v[230:231] op_sel_hi:[1,0,1]
	v_add_f32_dpp v238, v238, v238 quad_perm:[1,0,3,2] row_mask:0xf bank_mask:0xf bound_ctrl:1
	v_add_f32_dpp v234, v234, v234 row_mirror row_mask:0xf bank_mask:0xf bound_ctrl:1
	ds_read_b32 v240, v62 offset:18176
	ds_read_b128 v[10:13], v51 offset:17920
	ds_read_b128 v[6:9], v51 offset:16896
	s_waitcnt lgkmcnt(7)
	v_pk_fma_f32 v[36:37], v[32:33], v[234:235], v[54:55] op_sel_hi:[1,0,1]
	v_pk_fma_f32 v[34:35], v[30:31], v[234:235], v[56:57] op_sel_hi:[1,0,1]
	v_add_f32_dpp v238, v238, v238 quad_perm:[2,3,0,1] row_mask:0xf bank_mask:0xf bound_ctrl:1
	ds_write_b32 v49, v238 offset:2304
	ds_read_b128 v[224:227], v51 offset:19200
	s_waitcnt lgkmcnt(6)
	v_pk_mul_f32 v[232:233], v[28:29], v[36:37]
	v_pk_fma_f32 v[232:233], v[26:27], v[34:35], v[232:233]
	ds_read_b128 v[64:67], v51 offset:18688
	ds_read_b128 v[68:71], v51 offset:18944
	v_add_f32_e32 v234, v232, v233
	v_pk_mul_f32 v[236:237], v[24:25], v[36:37]
	v_pk_fma_f32 v[236:237], v[22:23], v[34:35], v[236:237]
	v_add_f32_dpp v234, v234, v234 quad_perm:[1,0,3,2] row_mask:0xf bank_mask:0xf bound_ctrl:1
	s_waitcnt lgkmcnt(5)
	v_pk_mul_f32 v[228:229], v[18:19], v[34:35]
	v_add_f32_e32 v238, v236, v237
	v_add_f32_dpp v234, v234, v234 quad_perm:[2,3,0,1] row_mask:0xf bank_mask:0xf bound_ctrl:1
	v_pk_mul_f32 v[230:231], v[20:21], v[36:37]
	v_pk_fma_f32 v[56:57], v[14:15], v[240:241], v[228:229] op_sel_hi:[1,0,1]
	v_add_f32_dpp v234, v234, v234 row_half_mirror row_mask:0xf bank_mask:0xf bound_ctrl:1
	v_pk_fma_f32 v[54:55], v[16:17], v[240:241], v[230:231] op_sel_hi:[1,0,1]
	v_add_f32_dpp v238, v238, v238 quad_perm:[1,0,3,2] row_mask:0xf bank_mask:0xf bound_ctrl:1
	v_add_f32_dpp v234, v234, v234 row_mirror row_mask:0xf bank_mask:0xf bound_ctrl:1
	ds_read_b32 v242, v62 offset:19712
	ds_read_b128 v[30:33], v51 offset:19456
	ds_read_b128 v[22:25], v51 offset:18432
	s_waitcnt lgkmcnt(7)
	v_pk_fma_f32 v[36:37], v[12:13], v[234:235], v[54:55] op_sel_hi:[1,0,1]
	v_pk_fma_f32 v[34:35], v[10:11], v[234:235], v[56:57] op_sel_hi:[1,0,1]
	v_add_f32_dpp v238, v238, v238 quad_perm:[2,3,0,1] row_mask:0xf bank_mask:0xf bound_ctrl:1
	ds_write_b32 v49, v238 offset:2560
	ds_read_b128 v[26:29], v51 offset:20736
	s_waitcnt lgkmcnt(6)
	v_pk_mul_f32 v[232:233], v[226:227], v[36:37]
	v_pk_fma_f32 v[232:233], v[224:225], v[34:35], v[232:233]
	ds_read_b128 v[18:21], v51 offset:20224
	ds_read_b128 v[14:17], v51 offset:20480
	v_add_f32_e32 v234, v232, v233
	v_pk_mul_f32 v[236:237], v[8:9], v[36:37]
	v_pk_fma_f32 v[236:237], v[6:7], v[34:35], v[236:237]
	v_add_f32_dpp v234, v234, v234 quad_perm:[1,0,3,2] row_mask:0xf bank_mask:0xf bound_ctrl:1
	s_waitcnt lgkmcnt(5)
	v_pk_mul_f32 v[228:229], v[64:65], v[34:35]
	v_add_f32_e32 v238, v236, v237
	v_add_f32_dpp v234, v234, v234 quad_perm:[2,3,0,1] row_mask:0xf bank_mask:0xf bound_ctrl:1
	v_pk_mul_f32 v[230:231], v[66:67], v[36:37]
	v_pk_fma_f32 v[56:57], v[68:69], v[242:243], v[228:229] op_sel_hi:[1,0,1]
	v_add_f32_dpp v234, v234, v234 row_half_mirror row_mask:0xf bank_mask:0xf bound_ctrl:1
	v_pk_fma_f32 v[54:55], v[70:71], v[242:243], v[230:231] op_sel_hi:[1,0,1]
	v_add_f32_dpp v238, v238, v238 quad_perm:[1,0,3,2] row_mask:0xf bank_mask:0xf bound_ctrl:1
	v_add_f32_dpp v234, v234, v234 row_mirror row_mask:0xf bank_mask:0xf bound_ctrl:1
	ds_read_b32 v240, v62 offset:21248
	ds_read_b128 v[10:13], v51 offset:20992
	ds_read_b128 v[6:9], v51 offset:19968
	s_waitcnt lgkmcnt(7)
	v_pk_fma_f32 v[36:37], v[32:33], v[234:235], v[54:55] op_sel_hi:[1,0,1]
	v_pk_fma_f32 v[34:35], v[30:31], v[234:235], v[56:57] op_sel_hi:[1,0,1]
	v_add_f32_dpp v238, v238, v238 quad_perm:[2,3,0,1] row_mask:0xf bank_mask:0xf bound_ctrl:1
	ds_write_b32 v49, v238 offset:2816
	ds_read_b128 v[224:227], v51 offset:22272
	s_waitcnt lgkmcnt(6)
	v_pk_mul_f32 v[232:233], v[28:29], v[36:37]
	v_pk_fma_f32 v[232:233], v[26:27], v[34:35], v[232:233]
	ds_read_b128 v[64:67], v51 offset:21760
	ds_read_b128 v[68:71], v51 offset:22016
	v_add_f32_e32 v234, v232, v233
	v_pk_mul_f32 v[236:237], v[24:25], v[36:37]
	v_pk_fma_f32 v[236:237], v[22:23], v[34:35], v[236:237]
	v_add_f32_dpp v234, v234, v234 quad_perm:[1,0,3,2] row_mask:0xf bank_mask:0xf bound_ctrl:1
	s_waitcnt lgkmcnt(5)
	v_pk_mul_f32 v[228:229], v[18:19], v[34:35]
	v_add_f32_e32 v238, v236, v237
	v_add_f32_dpp v234, v234, v234 quad_perm:[2,3,0,1] row_mask:0xf bank_mask:0xf bound_ctrl:1
	v_pk_mul_f32 v[230:231], v[20:21], v[36:37]
	v_pk_fma_f32 v[56:57], v[14:15], v[240:241], v[228:229] op_sel_hi:[1,0,1]
	v_add_f32_dpp v234, v234, v234 row_half_mirror row_mask:0xf bank_mask:0xf bound_ctrl:1
	v_pk_fma_f32 v[54:55], v[16:17], v[240:241], v[230:231] op_sel_hi:[1,0,1]
	v_add_f32_dpp v238, v238, v238 quad_perm:[1,0,3,2] row_mask:0xf bank_mask:0xf bound_ctrl:1
	v_add_f32_dpp v234, v234, v234 row_mirror row_mask:0xf bank_mask:0xf bound_ctrl:1
	ds_read_b32 v242, v62 offset:22784
	ds_read_b128 v[30:33], v51 offset:22528
	ds_read_b128 v[22:25], v51 offset:21504
	s_waitcnt lgkmcnt(7)
	v_pk_fma_f32 v[36:37], v[12:13], v[234:235], v[54:55] op_sel_hi:[1,0,1]
	v_pk_fma_f32 v[34:35], v[10:11], v[234:235], v[56:57] op_sel_hi:[1,0,1]
	v_add_f32_dpp v238, v238, v238 quad_perm:[2,3,0,1] row_mask:0xf bank_mask:0xf bound_ctrl:1
	ds_write_b32 v49, v238 offset:3072
	ds_read_b128 v[26:29], v51 offset:23808
	s_waitcnt lgkmcnt(6)
	v_pk_mul_f32 v[232:233], v[226:227], v[36:37]
	v_pk_fma_f32 v[232:233], v[224:225], v[34:35], v[232:233]
	ds_read_b128 v[18:21], v51 offset:23296
	ds_read_b128 v[14:17], v51 offset:23552
	v_add_f32_e32 v234, v232, v233
	v_pk_mul_f32 v[236:237], v[8:9], v[36:37]
	v_pk_fma_f32 v[236:237], v[6:7], v[34:35], v[236:237]
	v_add_f32_dpp v234, v234, v234 quad_perm:[1,0,3,2] row_mask:0xf bank_mask:0xf bound_ctrl:1
	s_waitcnt lgkmcnt(5)
	v_pk_mul_f32 v[228:229], v[64:65], v[34:35]
	v_add_f32_e32 v238, v236, v237
	v_add_f32_dpp v234, v234, v234 quad_perm:[2,3,0,1] row_mask:0xf bank_mask:0xf bound_ctrl:1
	v_pk_mul_f32 v[230:231], v[66:67], v[36:37]
	v_pk_fma_f32 v[56:57], v[68:69], v[242:243], v[228:229] op_sel_hi:[1,0,1]
	v_add_f32_dpp v234, v234, v234 row_half_mirror row_mask:0xf bank_mask:0xf bound_ctrl:1
	v_pk_fma_f32 v[54:55], v[70:71], v[242:243], v[230:231] op_sel_hi:[1,0,1]
	v_add_f32_dpp v238, v238, v238 quad_perm:[1,0,3,2] row_mask:0xf bank_mask:0xf bound_ctrl:1
	v_add_f32_dpp v234, v234, v234 row_mirror row_mask:0xf bank_mask:0xf bound_ctrl:1
	ds_read_b32 v240, v62 offset:24320
	ds_read_b128 v[10:13], v51 offset:24064
	ds_read_b128 v[6:9], v51 offset:23040
	s_waitcnt lgkmcnt(7)
	v_pk_fma_f32 v[36:37], v[32:33], v[234:235], v[54:55] op_sel_hi:[1,0,1]
	v_pk_fma_f32 v[34:35], v[30:31], v[234:235], v[56:57] op_sel_hi:[1,0,1]
	v_add_f32_dpp v238, v238, v238 quad_perm:[2,3,0,1] row_mask:0xf bank_mask:0xf bound_ctrl:1
	ds_write_b32 v49, v238 offset:3328
	s_waitcnt lgkmcnt(5)
	v_pk_mul_f32 v[232:233], v[28:29], v[36:37]
	v_pk_fma_f32 v[232:233], v[26:27], v[34:35], v[232:233]
	v_add_f32_e32 v234, v232, v233
	v_pk_mul_f32 v[236:237], v[24:25], v[36:37]
	v_pk_fma_f32 v[236:237], v[22:23], v[34:35], v[236:237]
	v_add_f32_dpp v234, v234, v234 quad_perm:[1,0,3,2] row_mask:0xf bank_mask:0xf bound_ctrl:1
	s_waitcnt lgkmcnt(2)
	v_pk_mul_f32 v[228:229], v[18:19], v[34:35]
	v_add_f32_e32 v238, v236, v237
	v_add_f32_dpp v234, v234, v234 quad_perm:[2,3,0,1] row_mask:0xf bank_mask:0xf bound_ctrl:1
	v_pk_mul_f32 v[230:231], v[20:21], v[36:37]
	v_pk_fma_f32 v[56:57], v[14:15], v[240:241], v[228:229] op_sel_hi:[1,0,1]
	v_add_f32_dpp v234, v234, v234 row_half_mirror row_mask:0xf bank_mask:0xf bound_ctrl:1
	v_pk_fma_f32 v[54:55], v[16:17], v[240:241], v[230:231] op_sel_hi:[1,0,1]
	v_add_f32_dpp v238, v238, v238 quad_perm:[1,0,3,2] row_mask:0xf bank_mask:0xf bound_ctrl:1
	v_add_f32_dpp v234, v234, v234 row_mirror row_mask:0xf bank_mask:0xf bound_ctrl:1
	s_waitcnt lgkmcnt(1)
	v_pk_fma_f32 v[36:37], v[12:13], v[234:235], v[54:55] op_sel_hi:[1,0,1]
	v_pk_fma_f32 v[34:35], v[10:11], v[234:235], v[56:57] op_sel_hi:[1,0,1]
	v_add_f32_dpp v238, v238, v238 quad_perm:[2,3,0,1] row_mask:0xf bank_mask:0xf bound_ctrl:1
	ds_write_b32 v49, v238 offset:3584
	v_pk_mul_f32 v[236:237], v[8:9], v[36:37]
	v_pk_fma_f32 v[236:237], v[6:7], v[34:35], v[236:237]
	v_add_f32_e32 v238, v236, v237
	s_nop 1
	v_add_f32_dpp v52, v238, v238 quad_perm:[1,0,3,2] row_mask:0xf bank_mask:0xf bound_ctrl:1
	s_nop 1
	v_mov_b32_dpp v64, v52 quad_perm:[2,3,0,1] row_mask:0xf bank_mask:0xf bound_ctrl:1
